# P9 tile output stores widened (V^T fragment dims remapped so a lane holds 8 contiguous dims: two 16-byte stores, 64 B contiguous per row) plus nt on the hgrn_b3 SS loads, on top of the nt read-once lo
# baseline (speedup 1.0000x reference)
; #define LAS __attribute__((address_space(3)))
; #define WG_BAR() asm volatile("s_waitcnt lgkmcnt(0)\n\ts_barrier" ::: "memory")
; #define MFMA16(a, b, c) __builtin_amdgcn_mfma_f32_16x16x32_bf16((a), (b), (c), 0, 0, 0)
; __device__ __forceinline__ float alibi_slope2(int g, int h) { return exp2f(-8.f * (float)(g * 16 + h + 1) / 48.f) * LOG2E; }
; __device__ __forceinline__ void attn_tile(Frame& F, const __amdgpu_buffer_rsrc_t wsr, LAS unsigned char* L, int grp, int h, int seq, int blk, const bf16x8 (&qf)[2], int sl_prev, int sl_cur, int sl_next) {
;     const int lane = F.lane, w = F.wave, r = lane & 15, g4 = lane >> 4;
;     const int dsh = 2 * grp, q0 = blk * 128, qw0 = q0 + 16 * w;
;     ...
;     const float sl2 = alibi_slope2(grp, h) * (float)(1 << dsh);
;     const float b4 = sl2 * (float)(4 * g4);
;     f32x4 st[10];
; #pragma unroll
;     for (int Tg = 0; Tg < 3; ++Tg) {
;         bf16x8 kf[3][2];
; #pragma unroll
;         for (int i = 0; i < 3; ++i) { const int rb = 16 * w + 16 * (3 * Tg + i); const LAS unsigned char* kb = L + AT_K + SLOT3(rb >> 7) * AT_SLOT;
; #pragma unroll
;             for (int ks = 0; ks < 2; ++ks) kf[i][ks] = ldfrag(kb, (rb & 127) + r, P144, ks, g4); }
; #pragma unroll
;         for (int i = 0; i < 3; ++i) st[3 * Tg + i] = MFMA16(kf[i][0], qf[0], ((f32x4){b4, b4, b4, b4}));
; #pragma unroll
;         for (int i = 0; i < 3; ++i) st[3 * Tg + i] = MFMA16(kf[i][1], qf[1], st[3 * Tg + i]);
;     }
;     const int lo_ = max(r, 128 - qw0) - 4 * g4, hi_ = r + 128 - 4 * g4;
; __device__ __forceinline__ void attn_prompt(Frame& F) {
;     LAS unsigned char* L = F.lds; const int tid = F.tid, lane = F.lane, w = F.wave, r = lane & 15, g4 = lane >> 4;
;     __syncthreads();
;     for (int e = tid; e < 6 * AT_SLOT / 16; e += 512) *(LAS v4u*)(L + e * 16) = (v4u){0u, 0u, 0u, 0u};
;     WG_BAR();
;     const __amdgpu_buffer_rsrc_t wsr = __builtin_amdgcn_make_buffer_rsrc((void*)F.ws, (short)0, (int)WS_END, 0x00020000);
;     v4u kA[2], vA[2], kB[2], vB[2]; bf16x8 qA[2], qB[2];
; #pragma unroll
;     for (int i = 0; i < 2; ++i) { kA[i] = vA[i] = kB[i] = vB[i] = (v4u){0u, 0u, 0u, 0u}; qA[i] = qB[i] = (bf16x8){0, 0, 0, 0, 0, 0, 0, 0}; }
;     int cui = 0, cs = 0, pui = 0, ps = 0, nstep = 0; bool running = true;
.LBB0_1647:
	s_movk_i32 s0, 0x90
	v_readlane_b32 s4, v245, 0
	v_mul_lo_u32 v100, v2, s0
	v_lshrrev_b32_e32 v2, 3, v3
	s_cmpk_lt_u32 s4, 0x200
	v_mul_lo_u32 v101, v2, s0
	s_cselect_b64 s[20:21], -1, 0
	s_and_b32 s0, s4, 0xfffffe00
	s_cmpk_eq_i32 s0, 0x200
	s_cselect_b64 s[0:1], -1, 0
	v_writelane_b32 v245, s0, 13
	s_and_b32 s3, s33, 0x70
	v_or_b32_e32 v3, s3, v94
	v_writelane_b32 v245, s1, 14
	v_mul_u32_u24_e32 v3, 0x90, v3
	v_readlane_b32 s5, v245, 8
	s_add_i32 s0, s5, 1
	s_lshl_b32 s1, s0, 4
	s_cmpk_lt_u32 s4, 0x1c0
	s_cselect_b64 s[24:25], -1, 0
	s_and_b32 s0, s0, 0x7fffff8
	s_cmp_eq_u32 s0, 8
	s_cselect_b64 s[6:7], -1, 0
	s_and_b32 s0, s1, 0x70
	v_add3_u32 v104, 0, v3, v98
	v_or_b32_e32 v3, s0, v94
	s_add_i32 s0, s5, 2
	s_lshl_b32 s1, s0, 4
	s_cmpk_lt_u32 s4, 0x180
	s_cselect_b64 s[36:37], -1, 0
	s_and_b32 s0, s0, 0x7fffff8
	v_writelane_b32 v245, s6, 27
	s_cmp_eq_u32 s0, 8
	v_mul_u32_u24_e32 v3, 0x90, v3
	v_writelane_b32 v245, s7, 28
	s_cselect_b64 s[6:7], -1, 0
	s_and_b32 s0, s1, 0x70
	v_add3_u32 v105, 0, v3, v98
	v_or_b32_e32 v3, s0, v94
	s_add_i32 s0, s5, 3
	s_lshl_b32 s1, s0, 4
	s_cmpk_lt_u32 s4, 0x140
	s_cselect_b64 s[40:41], -1, 0
	s_and_b32 s0, s0, 0x7fffff8
	v_writelane_b32 v245, s6, 19
	s_cmp_eq_u32 s0, 8
	v_mul_u32_u24_e32 v3, 0x90, v3
	v_writelane_b32 v245, s7, 20
	s_cselect_b64 s[6:7], -1, 0
	s_and_b32 s0, s1, 0x70
	v_add3_u32 v106, 0, v3, v98
	v_or_b32_e32 v3, s0, v94
	s_add_i32 s0, s5, 4
	s_lshl_b32 s1, s0, 4
	s_cmpk_lt_u32 s4, 0x100
	s_cselect_b64 s[54:55], -1, 0
	s_and_b32 s0, s0, 0x7fffff8
	v_writelane_b32 v245, s6, 15
	s_cmp_eq_u32 s0, 8
	v_mul_u32_u24_e32 v3, 0x90, v3
	v_writelane_b32 v245, s7, 16
	s_cselect_b64 s[6:7], -1, 0
	s_and_b32 s0, s1, 0x70
	v_add3_u32 v107, 0, v3, v98
	v_or_b32_e32 v3, s0, v94
	s_add_i32 s0, s5, 5
	s_lshl_b32 s1, s0, 4
	s_cmpk_lt_u32 s4, 0xc0
	s_cselect_b64 s[58:59], -1, 0
	s_and_b32 s0, s0, 0x7fffff8
	v_writelane_b32 v245, s6, 17
	s_cmp_eq_u32 s0, 8
	v_mul_u32_u24_e32 v3, 0x90, v3
	v_writelane_b32 v245, s7, 18
	s_cselect_b64 s[6:7], -1, 0
	s_and_b32 s0, s1, 0x70
	v_add3_u32 v108, 0, v3, v98
	v_or_b32_e32 v3, s0, v94
	s_add_i32 s0, s5, 6
	s_lshl_b32 s1, s0, 4
	s_cmpk_lt_u32 s4, 0x80
	s_cselect_b64 s[62:63], -1, 0
	s_and_b32 s0, s0, 0x7fffff8
	s_cmp_eq_u32 s0, 8
	v_mul_u32_u24_e32 v3, 0x90, v3
	s_cselect_b64 s[64:65], -1, 0
	s_and_b32 s0, s1, 0x70
	v_add3_u32 v109, 0, v3, v98
	v_or_b32_e32 v3, s0, v94
	s_add_i32 s0, s5, 7
	s_lshl_b32 s1, s0, 4
	s_cmp_lt_u32 s4, 64
	s_cselect_b64 s[66:67], -1, 0
	s_and_b32 s0, s0, 0x7fffff8
	s_cmp_eq_u32 s0, 8
	v_mul_u32_u24_e32 v3, 0x90, v3
	s_cselect_b64 s[68:69], -1, 0
	s_and_b32 s0, s1, 0x70
	v_add3_u32 v110, 0, v3, v98
	v_or_b32_e32 v3, s0, v94
	s_add_i32 s0, s5, 8
	s_lshl_b32 s1, s0, 4
	s_and_b32 s0, s0, 0x7fffff8
	s_cmp_eq_u32 s0, 8
	v_mul_u32_u24_e32 v3, 0x90, v3
	s_cselect_b64 s[70:71], -1, 0
	s_and_b32 s0, s1, 0x70
	v_add3_u32 v111, 0, v3, v98
	v_or_b32_e32 v3, s0, v94
	v_lshrrev_b32_e32 v2, 2, v160
	v_mul_u32_u24_e32 v3, 0x90, v3
	v_and_b32_e32 v102, 12, v2
	v_writelane_b32 v245, s6, 23
	v_add3_u32 v112, 0, v3, v98
	v_or_b32_e32 v3, 0x80, v94
	v_writelane_b32 v245, s7, 24
	s_movk_i32 s6, 0x80
	v_sub_u32_e32 v4, v3, v102
	s_movk_i32 s4, 0x81
	v_cmp_gt_u32_e64 s[0:1], s6, v4
	v_cmp_gt_u32_e64 s[6:7], s4, v4
	s_movk_i32 s4, 0x82
	v_cmp_gt_u32_e64 s[8:9], s4, v4
	s_movk_i32 s4, 0x83
	v_cmp_gt_u32_e64 s[10:11], s4, v4
	s_add_i32 s4, s33, 16
	v_or_b32_e32 v5, s3, v2
	s_and_b32 s3, s4, 0x7fffff80
	v_lshlrev_b32_e32 v4, 3, v160
	s_cmpk_eq_i32 s3, 0x80
	v_and_b32_e32 v4, 24, v4
	v_mul_u32_u24_e32 v5, 0x90, v5
	s_cselect_b64 s[72:73], -1, 0
	s_and_b32 s3, s4, 0x70
	v_add3_u32 v113, 0, v5, v4
	v_or_b32_e32 v5, s3, v2
	s_add_i32 s3, s33, 32
	s_add_i32 s4, s33, 48
	s_and_b32 s5, s3, 0x7fffff80
	s_cmpk_eq_i32 s5, 0x80
	v_mul_u32_u24_e32 v5, 0x90, v5
	s_cselect_b64 s[74:75], -1, 0
	s_and_b32 s3, s3, 0x70
	v_add3_u32 v114, 0, v5, v4
	v_or_b32_e32 v5, s3, v2
	s_and_b32 s3, s4, 0x7fffff80
	s_cmpk_eq_i32 s3, 0x80
	v_mul_u32_u24_e32 v5, 0x90, v5
	s_cselect_b64 s[76:77], -1, 0
	s_and_b32 s3, s4, 0x70
	v_add3_u32 v115, 0, v5, v4
	v_or_b32_e32 v5, s3, v2
	s_add_i32 s3, s33, 64
	s_add_i32 s4, s33, 0x50
	s_and_b32 s5, s3, 0x7fffff80
	s_cmpk_eq_i32 s5, 0x80
	v_mul_u32_u24_e32 v5, 0x90, v5
	s_cselect_b64 s[78:79], -1, 0
	s_and_b32 s3, s3, 0x70
	v_add3_u32 v116, 0, v5, v4
	v_or_b32_e32 v5, s3, v2
	s_and_b32 s3, s4, 0x7fffff80
	s_cmpk_eq_i32 s3, 0x80
	v_mul_u32_u24_e32 v5, 0x90, v5
	s_cselect_b64 s[80:81], -1, 0
	s_and_b32 s3, s4, 0x70
	v_add3_u32 v117, 0, v5, v4
	v_or_b32_e32 v5, s3, v2
	s_add_i32 s3, s33, 0x60
	s_add_i32 s4, s33, 0x70
	s_and_b32 s5, s3, 0x7fffff80
	s_cmpk_eq_i32 s5, 0x80
	v_mul_u32_u24_e32 v5, 0x90, v5
	s_cselect_b64 s[82:83], -1, 0
	s_and_b32 s3, s3, 0x70
	v_add3_u32 v118, 0, v5, v4
	v_or_b32_e32 v5, s3, v2
	s_and_b32 s3, s4, 0x7fffff80
	s_cmpk_eq_i32 s3, 0x80
	v_mul_u32_u24_e32 v5, 0x90, v5
	s_cselect_b64 s[84:85], -1, 0
	s_and_b32 s3, s4, 0x70
	v_add3_u32 v119, 0, v5, v4
	v_or_b32_e32 v5, s3, v2
	s_add_i32 s3, s33, 0x90
	s_and_b32 s4, s3, 0x7fffff80
	s_cmpk_eq_i32 s4, 0x80
	s_cselect_b64 s[86:87], -1, 0
	s_and_b32 s3, s3, 0x70
	v_or_b32_e32 v2, s3, v2
	v_mul_u32_u24_e32 v2, 0x90, v2
	v_mul_u32_u24_e32 v5, 0x90, v5
	v_add3_u32 v121, 0, v2, v4
	v_mbcnt_lo_u32_b32 v2, -1, 0
	s_mov_b32 s93, 3
	s_mov_b32 s92, 2
	v_cvt_f32_ubyte0_e32 v103, v102
	s_mov_b32 s22, 0
	s_mov_b32 s56, 1
	v_add3_u32 v120, 0, v5, v4
	v_lshlrev_b32_e32 v122, 1, v102
	v_cmp_gt_u32_e64 s[12:13], 16, v160
	v_cvt_f32_ubyte0_e32 v123, v3
	v_add_u32_e32 v124, 0, v95
	v_add_u32_e32 v125, 0x12000, v101
	v_add_u32_e32 v126, 0x4800, v101
	v_add_u32_e32 v127, 0x12000, v100
	v_add_u32_e32 v128, 0x4800, v100
	v_mov_b32_e32 v60, 0
	s_mov_b32 s95, 0x42400000
	v_mov_b32_e32 v129, 0x42800000
	v_mov_b32_e32 v130, 0xff800000
	v_mbcnt_hi_u32_b32 v131, -1, v2
	v_mov_b32_e32 v132, 0
	s_mov_b32 s27, 0
	s_mov_b32 s23, 0
	s_mov_b32 s26, 2
	s_mov_b32 s47, 0
	s_waitcnt vmcnt(0)
; __device__ __forceinline__ void attn_tile(Frame& F, const __amdgpu_buffer_rsrc_t wsr, LAS unsigned char* L, int grp, int h, int seq, int blk, const bf16x8 (&qf)[2], int sl_prev, int sl_cur, int sl_next) {
;     const int lane = F.lane, w = F.wave, r = lane & 15, g4 = lane >> 4;
;     const int dsh = 2 * grp, q0 = blk * 128, qw0 = q0 + 16 * w;
;     ...
;     const float sl2 = alibi_slope2(grp, h) * (float)(1 << dsh);
;     const float b4 = sl2 * (float)(4 * g4);
;     f32x4 st[10];
; #pragma unroll
;     for (int Tg = 0; Tg < 3; ++Tg) {
;         bf16x8 kf[3][2];
; #pragma unroll
;         for (int i = 0; i < 3; ++i) { const int rb = 16 * w + 16 * (3 * Tg + i); const LAS unsigned char* kb = L + AT_K + SLOT3(rb >> 7) * AT_SLOT;
; #pragma unroll
;             for (int ks = 0; ks < 2; ++ks) kf[i][ks] = ldfrag(kb, (rb & 127) + r, P144, ks, g4); }
; #pragma unroll
;         for (int i = 0; i < 3; ++i) st[3 * Tg + i] = MFMA16(kf[i][0], qf[0], ((f32x4){b4, b4, b4, b4}));
; #pragma unroll
;         for (int i = 0; i < 3; ++i) st[3 * Tg + i] = MFMA16(kf[i][1], qf[1], st[3 * Tg + i]);
;     }
;     const int lo_ = max(r, 128 - qw0) - 4 * g4, hi_ = r + 128 - 4 * g4;
;     float mx = -INFINITY;
; #pragma unroll
;     for (int T = 0; T < 9; ++T)
; #pragma unroll
;         for (int e = 0; e < 4; ++e) { float y = __builtin_fmaf(sl2, (float)(16 * T + e), st[T][e]);
;             if ((16 * T + e) < lo_) y = -INFINITY;
;             if (T == 8) { if ((16 * T + e) > hi_) y = -INFINITY; }
;             st[T][e] = y; mx = fmaxf(mx, y); }
;     mx = fmaxf(mx, __shfl_xor(mx, 16)); mx = fmaxf(mx, __shfl_xor(mx, 32));
;     float lsum = 0.f;
; #pragma unroll
;     for (int T = 0; T < 9; ++T)
; #pragma unroll
;         for (int e = 0; e < 4; ++e) { const float p = __builtin_amdgcn_exp2f(st[T][e] - mx); st[T][e] = p; lsum += p; }
;     st[9] = (f32x4){0.f, 0.f, 0.f, 0.f};
;     lsum += __shfl_xor(lsum, 16); lsum += __shfl_xor(lsum, 32);
;     mx -= sl2 * (float)(r + 128);
;     f32x4 oa[4];
; #pragma unroll
;     for (int dt = 0; dt < 4; ++dt) oa[dt] = (f32x4){0.f, 0.f, 0.f, 0.f};
; #pragma unroll
;     for (int u = 0; u < 5; ++u) {
;         const v4u pw = (v4u){pk2(st[2 * u][0], st[2 * u][1]), pk2(st[2 * u][2], st[2 * u][3]), pk2(st[2 * u + 1][0], st[2 * u + 1][1]), pk2(st[2 * u + 1][2], st[2 * u + 1][3])};
;         const bf16x8 pf = __builtin_bit_cast(bf16x8, pw);
	v_mov_b64_e32 v[2:3], v[18:19]
	v_mov_b64_e32 v[4:5], v[20:21]
	v_mov_b64_e32 v[6:7], v[22:23]
	v_mov_b64_e32 v[8:9], v[24:25]
	v_mov_b64_e32 v[246:247], v[10:11]
	v_mov_b64_e32 v[248:249], v[12:13]
	v_mov_b64_e32 v[250:251], v[14:15]
	v_mov_b64_e32 v[252:253], v[16:17]
	s_mov_b32 s98, 0
	v_and_b32_e32 v185, 15, v160
	v_lshrrev_b32_e32 v186, 4, v160
	v_lshlrev_b32_e32 v186, 2, v186
	v_mov_b32_e32 v191, 0xff800000
	v_mul_u32_u24_e32 v170, 0x90, v185
	v_lshl_add_u32 v170, v186, 2, v170
	v_lshrrev_b32_e32 v171, 2, v185
	v_add_u32_e32 v171, v171, v186
	v_mul_u32_u24_e32 v171, 0x90, v171
	v_and_b32_e32 v172, 3, v185
	v_lshl_add_u32 v171, v172, 4, v171
	v_cvt_f32_u32_e32 v172, v186
	v_add_f32_e32 v173, 1.0, v172
	v_add_f32_e32 v174, 2.0, v172
	v_add_f32_e32 v175, 1.0, v174
	v_add_u32_e32 v184, 0, v186
	v_cmp_lt_u32_e32 vcc, v184, v185
	s_nop 1
	v_cndmask_b32_e32 v176, 0, v191, vcc
	v_cmp_gt_u32_e32 vcc, v184, v185
	s_nop 1
	v_cndmask_b32_e32 v180, 0, v191, vcc
	v_add_u32_e32 v184, 1, v186
	v_cmp_lt_u32_e32 vcc, v184, v185
	s_nop 1
	v_cndmask_b32_e32 v177, 0, v191, vcc
	v_cmp_gt_u32_e32 vcc, v184, v185
	s_nop 1
	v_cndmask_b32_e32 v181, 0, v191, vcc
	v_add_u32_e32 v184, 2, v186
	v_cmp_lt_u32_e32 vcc, v184, v185
	s_nop 1
	v_cndmask_b32_e32 v178, 0, v191, vcc
	v_cmp_gt_u32_e32 vcc, v184, v185
	s_nop 1
	v_cndmask_b32_e32 v182, 0, v191, vcc
	v_add_u32_e32 v184, 3, v186
	v_cmp_lt_u32_e32 vcc, v184, v185
	s_nop 1
	v_cndmask_b32_e32 v179, 0, v191, vcc
	v_cmp_gt_u32_e32 vcc, v184, v185
	s_nop 1
	v_cndmask_b32_e32 v183, 0, v191, vcc
	v_add_u32_e32 v184, 0x80, v185
	v_cvt_f32_u32_e32 v184, v184
	v_subrev_u32_e32 v187, 24, v160
	v_min_u32_e32 v187, v160, v187
	v_mul_u32_u24_e32 v187, 0x900, v187
	v_lshlrev_b32_e32 v188, 1, v186
	v_xor_b32_e32 v189, 16, v160
	v_lshlrev_b32_e32 v189, 2, v189
	v_xor_b32_e32 v190, 32, v160
	v_lshlrev_b32_e32 v190, 2, v190
	s_branch .LBB0_1651

.LBB0_1657:
	s_mov_b64 s[4:5], -1
	v_readfirstlane_b32 s57, v0
	v_readfirstlane_b32 s15, v0
	v_readfirstlane_b32 s61, v0
	v_readfirstlane_b32 s42, v0
	v_readfirstlane_b32 s16, v0
	v_readfirstlane_b32 s39, v0
	v_readfirstlane_b32 s43, v0
	v_readfirstlane_b32 s48, v0
	v_readfirstlane_b32 s49, v0
	v_readfirstlane_b32 s94, v0
	s_andn2_b64 vcc, exec, s[34:35]
	v_readfirstlane_b32 s34, v0
	s_cbranch_vccnz .LBB0_1650
	s_bfe_u32 s99, s98, 0x10001
	s_bfe_u32 s100, s98, 0x10002
	s_bfe_u32 s101, s98, 0x10003
	s_add_u32 s99, s99, s101
	s_mul_i32 s99, s99, 3
	s_mul_i32 s100, s100, 6
	s_add_u32 s99, s99, s100
	s_cmp_eq_u32 s99, 12
	s_cbranch_scc1 .Lat_a12
	s_cmp_eq_u32 s99, 9
	s_cbranch_scc1 .Lat_a9
	s_cmp_eq_u32 s99, 6
	s_cbranch_scc1 .Lat_a6
	s_cmp_eq_u32 s99, 3
	s_cbranch_scc1 .Lat_a3
	s_waitcnt vmcnt(0)
	s_branch .Lat_adone
.Lat_a12:
	s_waitcnt vmcnt(12)
	s_branch .Lat_adone
.Lat_a9:
	s_waitcnt vmcnt(9)
	s_branch .Lat_adone

.Lat_a3:
	s_waitcnt vmcnt(3)

; #define LAS __attribute__((address_space(3)))
; __device__ __forceinline__ void attn_tile(Frame& F, const __amdgpu_buffer_rsrc_t wsr, LAS unsigned char* L, int grp, int h, int seq, int blk, const bf16x8 (&qf)[2], int sl_prev, int sl_cur, int sl_next) {
;     ...
;     for (int Tg = 0; Tg < 3; ++Tg) {
;         bf16x8 kf[3][2];
; #pragma unroll
;         for (int i = 0; i < 3; ++i) { const int rb = 16 * w + 16 * (3 * Tg + i); const LAS unsigned char* kb = L + AT_K + SLOT3(rb >> 7) * AT_SLOT;
; #pragma unroll
;             for (int ks = 0; ks < 2; ++ks) kf[i][ks] = ldfrag(kb, (rb & 127) + r, P144, ks, g4); }
; #pragma unroll
;         for (int i = 0; i < 3; ++i) st[3 * Tg + i] = MFMA16(kf[i][0], qf[0], ((f32x4){b4, b4, b4, b4}));
; #pragma unroll
;         for (int i = 0; i < 3; ++i) st[3 * Tg + i] = MFMA16(kf[i][1], qf[1], st[3 * Tg + i]);
;     }
;     const int lo_ = max(r, 128 - qw0) - 4 * g4, hi_ = r + 128 - 4 * g4;
;     float mx = -INFINITY;
; #pragma unroll
;     for (int T = 0; T < 9; ++T)
; #pragma unroll
;         for (int e = 0; e < 4; ++e) { float y = __builtin_fmaf(sl2, (float)(16 * T + e), st[T][e]);
;             if ((16 * T + e) < lo_) y = -INFINITY;
;             if (T == 8) { if ((16 * T + e) > hi_) y = -INFINITY; }
;             st[T][e] = y; mx = fmaxf(mx, y); }
;     mx = fmaxf(mx, __shfl_xor(mx, 16)); mx = fmaxf(mx, __shfl_xor(mx, 32));
;     float lsum = 0.f;
; #pragma unroll
;     for (int T = 0; T < 9; ++T)
; #pragma unroll
;         for (int e = 0; e < 4; ++e) { const float p = __builtin_amdgcn_exp2f(st[T][e] - mx); st[T][e] = p; lsum += p; }
;     st[9] = (f32x4){0.f, 0.f, 0.f, 0.f};
;     lsum += __shfl_xor(lsum, 16); lsum += __shfl_xor(lsum, 32);
;     mx -= sl2 * (float)(r + 128);
;     f32x4 oa[4];
; #pragma unroll
;     for (int dt = 0; dt < 4; ++dt) oa[dt] = (f32x4){0.f, 0.f, 0.f, 0.f};
; #pragma unroll
;     for (int u = 0; u < 5; ++u) {
;         const v4u pw = (v4u){pk2(st[2 * u][0], st[2 * u][1]), pk2(st[2 * u][2], st[2 * u][3]), pk2(st[2 * u + 1][0], st[2 * u + 1][1]), pk2(st[2 * u + 1][2], st[2 * u + 1][3])};
;         const bf16x8 pf = __builtin_bit_cast(bf16x8, pw);
;         const int v0 = 16 * w + 32 * u, v1 = v0 + 16;
;         const LAS unsigned char* vlo = L + AT_V + SLOT3(v0 >> 7) * AT_SLOT + ((v0 & 127) + 4 * g4 + (r >> 2)) * P144 + 8 * (r & 3);
.Lat_nofirst:
	s_nop 0
	s_waitcnt lgkmcnt(4)
	v_mfma_f32_16x16x32_bf16 v[192:195], v[62:65], v[18:21], v[192:195]
	v_mfma_f32_16x16x32_bf16 v[192:195], v[66:69], v[22:25], v[192:195]
	ds_read_b128 v[62:65], v145
	ds_read_b128 v[66:69], v145 offset:64
	s_waitcnt lgkmcnt(4)
	v_mfma_f32_16x16x32_bf16 v[196:199], v[70:73], v[18:21], v[196:199]
	v_mfma_f32_16x16x32_bf16 v[196:199], v[74:77], v[22:25], v[196:199]
	ds_read_b128 v[70:73], v146
	ds_read_b128 v[74:77], v146 offset:64
	s_waitcnt lgkmcnt(4)
	v_mfma_f32_16x16x32_bf16 v[200:203], v[78:81], v[18:21], v[200:203]
	v_mfma_f32_16x16x32_bf16 v[200:203], v[82:85], v[22:25], v[200:203]
	ds_read_b128 v[78:81], v147
	ds_read_b128 v[82:85], v147 offset:64
	s_waitcnt lgkmcnt(4)
	v_mfma_f32_16x16x32_bf16 v[204:207], v[62:65], v[18:21], v[204:207]
	v_mfma_f32_16x16x32_bf16 v[204:207], v[66:69], v[22:25], v[204:207]
	ds_read_b128 v[62:65], v148
	ds_read_b128 v[66:69], v148 offset:64
	s_waitcnt lgkmcnt(4)
	v_mfma_f32_16x16x32_bf16 v[208:211], v[70:73], v[18:21], v[208:211]
	v_mfma_f32_16x16x32_bf16 v[208:211], v[74:77], v[22:25], v[208:211]
	ds_read_b128 v[70:73], v149
	ds_read_b128 v[74:77], v149 offset:64
	s_waitcnt lgkmcnt(4)
	v_mfma_f32_16x16x32_bf16 v[212:215], v[78:81], v[18:21], v[212:215]
	v_mfma_f32_16x16x32_bf16 v[212:215], v[82:85], v[22:25], v[212:215]
	ds_read_b128 v[78:81], v150
	ds_read_b128 v[82:85], v150 offset:64
	s_waitcnt lgkmcnt(4)
	v_mfma_f32_16x16x32_bf16 v[216:219], v[62:65], v[18:21], v[216:219]
	v_mfma_f32_16x16x32_bf16 v[216:219], v[66:69], v[22:25], v[216:219]
	s_waitcnt lgkmcnt(2)
	v_mfma_f32_16x16x32_bf16 v[220:223], v[70:73], v[18:21], v[220:223]
	v_mfma_f32_16x16x32_bf16 v[220:223], v[74:77], v[22:25], v[220:223]
	s_waitcnt lgkmcnt(0)
	v_mfma_f32_16x16x32_bf16 v[224:227], v[78:81], v[18:21], v[224:227]
	v_mfma_f32_16x16x32_bf16 v[224:227], v[82:85], v[22:25], v[224:227]
	ds_read_b64_tr_b16 v[62:63], v232 offset:55296
	ds_read_b64_tr_b16 v[64:65], v233 offset:55296
	ds_read_b64_tr_b16 v[66:67], v232 offset:55304
	ds_read_b64_tr_b16 v[68:69], v233 offset:55304
	ds_read_b64_tr_b16 v[70:71], v232 offset:55360
	ds_read_b64_tr_b16 v[72:73], v233 offset:55360
	ds_read_b64_tr_b16 v[74:75], v232 offset:55368
	ds_read_b64_tr_b16 v[76:77], v233 offset:55368
	v_max3_f32 v86, v192, v193, v194
	v_max3_f32 v86, v86, v195, v196
	v_max3_f32 v86, v86, v197, v198
	v_max3_f32 v86, v86, v199, v200
	v_max3_f32 v86, v86, v201, v202
	v_max3_f32 v86, v86, v203, v204
	v_max3_f32 v86, v86, v205, v206
	v_max3_f32 v86, v86, v207, v208
	v_max3_f32 v86, v86, v209, v210
	v_max3_f32 v86, v86, v211, v212
	v_max3_f32 v86, v86, v213, v214
	v_max3_f32 v86, v86, v215, v216
	v_max3_f32 v86, v86, v217, v218
	v_max3_f32 v86, v86, v219, v220
	v_max3_f32 v86, v86, v221, v222
	v_max3_f32 v86, v86, v223, v224
	v_max3_f32 v86, v86, v225, v226
	v_max_f32_e32 v86, v86, v227
	ds_bpermute_b32 v58, v189, v86
	s_waitcnt lgkmcnt(0)
	v_max_f32_e32 v86, v86, v58
	ds_bpermute_b32 v58, v190, v86
	s_waitcnt lgkmcnt(0)
	v_max_f32_e32 v86, v86, v58
	v_mov_b32_e32 v254, 0
	v_mov_b32_e32 v255, 0
	v_pk_add_f32 v[192:193], v[192:193], v[86:87] op_sel_hi:[1,0] neg_lo:[0,1] neg_hi:[0,1]
	v_pk_add_f32 v[194:195], v[194:195], v[86:87] op_sel_hi:[1,0] neg_lo:[0,1] neg_hi:[0,1]
	v_pk_add_f32 v[196:197], v[196:197], v[86:87] op_sel_hi:[1,0] neg_lo:[0,1] neg_hi:[0,1]
	v_pk_add_f32 v[198:199], v[198:199], v[86:87] op_sel_hi:[1,0] neg_lo:[0,1] neg_hi:[0,1]
	v_pk_add_f32 v[200:201], v[200:201], v[86:87] op_sel_hi:[1,0] neg_lo:[0,1] neg_hi:[0,1]
	v_pk_add_f32 v[202:203], v[202:203], v[86:87] op_sel_hi:[1,0] neg_lo:[0,1] neg_hi:[0,1]
	v_pk_add_f32 v[204:205], v[204:205], v[86:87] op_sel_hi:[1,0] neg_lo:[0,1] neg_hi:[0,1]
	v_pk_add_f32 v[206:207], v[206:207], v[86:87] op_sel_hi:[1,0] neg_lo:[0,1] neg_hi:[0,1]
	v_pk_add_f32 v[208:209], v[208:209], v[86:87] op_sel_hi:[1,0] neg_lo:[0,1] neg_hi:[0,1]
	v_pk_add_f32 v[210:211], v[210:211], v[86:87] op_sel_hi:[1,0] neg_lo:[0,1] neg_hi:[0,1]
	v_pk_add_f32 v[212:213], v[212:213], v[86:87] op_sel_hi:[1,0] neg_lo:[0,1] neg_hi:[0,1]
	v_pk_add_f32 v[214:215], v[214:215], v[86:87] op_sel_hi:[1,0] neg_lo:[0,1] neg_hi:[0,1]
	v_pk_add_f32 v[216:217], v[216:217], v[86:87] op_sel_hi:[1,0] neg_lo:[0,1] neg_hi:[0,1]
	v_pk_add_f32 v[218:219], v[218:219], v[86:87] op_sel_hi:[1,0] neg_lo:[0,1] neg_hi:[0,1]
	v_pk_add_f32 v[220:221], v[220:221], v[86:87] op_sel_hi:[1,0] neg_lo:[0,1] neg_hi:[0,1]
	v_pk_add_f32 v[222:223], v[222:223], v[86:87] op_sel_hi:[1,0] neg_lo:[0,1] neg_hi:[0,1]
	v_pk_add_f32 v[224:225], v[224:225], v[86:87] op_sel_hi:[1,0] neg_lo:[0,1] neg_hi:[0,1]
	v_pk_add_f32 v[226:227], v[226:227], v[86:87] op_sel_hi:[1,0] neg_lo:[0,1] neg_hi:[0,1]
	v_exp_f32_e32 v192, v192
	v_exp_f32_e32 v193, v193
	v_exp_f32_e32 v194, v194
	v_exp_f32_e32 v195, v195
	v_exp_f32_e32 v196, v196
	v_exp_f32_e32 v197, v197
	v_exp_f32_e32 v198, v198
	v_exp_f32_e32 v199, v199
	v_pk_add_f32 v[254:255], v[254:255], v[192:193]
	v_pk_add_f32 v[254:255], v[254:255], v[194:195]
	v_cvt_pk_bf16_f32 v142, v192, v193
	v_cvt_pk_bf16_f32 v143, v194, v195
	v_exp_f32_e32 v200, v200
	v_exp_f32_e32 v201, v201
	v_exp_f32_e32 v202, v202
	v_exp_f32_e32 v203, v203
	v_pk_add_f32 v[254:255], v[254:255], v[196:197]
	v_pk_add_f32 v[254:255], v[254:255], v[198:199]
	v_cvt_pk_bf16_f32 v144, v196, v197
	v_cvt_pk_bf16_f32 v145, v198, v199
	v_exp_f32_e32 v204, v204
	v_exp_f32_e32 v205, v205
	v_exp_f32_e32 v206, v206
	v_exp_f32_e32 v207, v207
	v_pk_add_f32 v[254:255], v[254:255], v[200:201]
	v_pk_add_f32 v[254:255], v[254:255], v[202:203]
	v_cvt_pk_bf16_f32 v146, v200, v201
	v_cvt_pk_bf16_f32 v147, v202, v203
	v_exp_f32_e32 v208, v208
	v_exp_f32_e32 v209, v209
; #define LAS __attribute__((address_space(3)))
; __device__ __forceinline__ void attn_tile(Frame& F, const __amdgpu_buffer_rsrc_t wsr, LAS unsigned char* L, int grp, int h, int seq, int blk, const bf16x8 (&qf)[2], int sl_prev, int sl_cur, int sl_next) {
;     ...
;     for (int T = 0; T < 9; ++T)
; #pragma unroll
;         for (int e = 0; e < 4; ++e) { const float p = __builtin_amdgcn_exp2f(st[T][e] - mx); st[T][e] = p; lsum += p; }
;     st[9] = (f32x4){0.f, 0.f, 0.f, 0.f};
;     lsum += __shfl_xor(lsum, 16); lsum += __shfl_xor(lsum, 32);
;     mx -= sl2 * (float)(r + 128);
;     f32x4 oa[4];
; #pragma unroll
;     for (int dt = 0; dt < 4; ++dt) oa[dt] = (f32x4){0.f, 0.f, 0.f, 0.f};
; #pragma unroll
;     for (int u = 0; u < 5; ++u) {
;         const v4u pw = (v4u){pk2(st[2 * u][0], st[2 * u][1]), pk2(st[2 * u][2], st[2 * u][3]), pk2(st[2 * u + 1][0], st[2 * u + 1][1]), pk2(st[2 * u + 1][2], st[2 * u + 1][3])};
;         const bf16x8 pf = __builtin_bit_cast(bf16x8, pw);
;         const int v0 = 16 * w + 32 * u, v1 = v0 + 16;
;         const LAS unsigned char* vlo = L + AT_V + SLOT3(v0 >> 7) * AT_SLOT + ((v0 & 127) + 4 * g4 + (r >> 2)) * P144 + 8 * (r & 3);
;         const LAS unsigned char* vhi = L + AT_V + SLOT3(v1 >> 7) * AT_SLOT + ((v1 & 127) + 4 * g4 + (r >> 2)) * P144 + 8 * (r & 3);
; #pragma unroll
;         for (int dt = 0; dt < 4; ++dt) {
;             const s16x4 lo = tr16(vlo + 32 * dt), hi = tr16(vhi + 32 * dt);
;             const bf16x8 vf = (bf16x8){lo[0], lo[1], lo[2], lo[3], hi[0], hi[1], hi[2], hi[3]};
;             oa[dt] = MFMA16(vf, pf, oa[dt]);
;         }
;     }
;     const float inv = 1.f / lsum;
;     const int m = qw0 + r, res = seq & ((1 << dsh) - 1), b = seq >> dsh;
;     const unsigned nrow = (unsigned)(b * SEQ + (m << dsh) + res);
;     const unsigned ob = (nrow * DM + h * 64 + 4 * g4) * 2u; const int obase = (int)(unsigned)(WS_OG + (size_t)grp * QKV_STRIDE);
; #pragma unroll
;     for (int dt = 0; dt < 4; ++dt) __builtin_amdgcn_raw_buffer_store_b64((v2u){pk2(oa[dt][0] * inv, oa[dt][1] * inv), pk2(oa[dt][2] * inv, oa[dt][3] * inv)}, wsr, (int)(ob + 32u * dt), obase, 0);
;     if (g4 == 0) __builtin_amdgcn_raw_buffer_store_b32(__float_as_uint((mx + __log2f(lsum)) * LN2), wsr, (int)((((unsigned)grp * MT + nrow) * 16 + h) * 4u), (int)(unsigned)WS_LSE, 0);
	v_exp_f32_e32 v210, v210
	v_exp_f32_e32 v211, v211
	v_pk_add_f32 v[254:255], v[254:255], v[204:205]
	v_pk_add_f32 v[254:255], v[254:255], v[206:207]
	v_cvt_pk_bf16_f32 v148, v204, v205
	v_cvt_pk_bf16_f32 v149, v206, v207
	v_exp_f32_e32 v212, v212
	v_exp_f32_e32 v213, v213
	v_exp_f32_e32 v214, v214
	v_exp_f32_e32 v215, v215
	v_pk_add_f32 v[254:255], v[254:255], v[208:209]
	v_pk_add_f32 v[254:255], v[254:255], v[210:211]
	v_cvt_pk_bf16_f32 v150, v208, v209
	v_cvt_pk_bf16_f32 v151, v210, v211
	v_exp_f32_e32 v216, v216
	v_exp_f32_e32 v217, v217
	v_exp_f32_e32 v218, v218
	v_exp_f32_e32 v219, v219
	v_pk_add_f32 v[254:255], v[254:255], v[212:213]
	v_pk_add_f32 v[254:255], v[254:255], v[214:215]
	v_cvt_pk_bf16_f32 v152, v212, v213
	v_cvt_pk_bf16_f32 v153, v214, v215
	v_exp_f32_e32 v220, v220
	v_exp_f32_e32 v221, v221
	v_exp_f32_e32 v222, v222
	v_exp_f32_e32 v223, v223
	v_pk_add_f32 v[254:255], v[254:255], v[216:217]
	v_pk_add_f32 v[254:255], v[254:255], v[218:219]
	v_cvt_pk_bf16_f32 v154, v216, v217
	v_cvt_pk_bf16_f32 v155, v218, v219
	v_exp_f32_e32 v224, v224
	v_exp_f32_e32 v225, v225
	v_exp_f32_e32 v226, v226
	v_exp_f32_e32 v227, v227
	v_pk_add_f32 v[254:255], v[254:255], v[220:221]
	v_pk_add_f32 v[254:255], v[254:255], v[222:223]
	v_cvt_pk_bf16_f32 v156, v220, v221
	v_cvt_pk_bf16_f32 v157, v222, v223
	s_nop 0
	v_pk_add_f32 v[254:255], v[254:255], v[224:225]
	v_pk_add_f32 v[254:255], v[254:255], v[226:227]
	v_cvt_pk_bf16_f32 v162, v224, v225
	v_cvt_pk_bf16_f32 v163, v226, v227
	v_mov_b32_e32 v164, 0
	v_mov_b32_e32 v165, 0
	v_add_f32_e32 v89, v254, v255
	ds_read_b64_tr_b16 v[208:209], v234 offset:55296
	ds_read_b64_tr_b16 v[210:211], v235 offset:55296
	ds_read_b64_tr_b16 v[212:213], v234 offset:55304
	ds_read_b64_tr_b16 v[214:215], v235 offset:55304
	ds_read_b64_tr_b16 v[216:217], v234 offset:55360
	ds_read_b64_tr_b16 v[218:219], v235 offset:55360
	ds_read_b64_tr_b16 v[220:221], v234 offset:55368
	ds_read_b64_tr_b16 v[222:223], v235 offset:55368
	ds_bpermute_b32 v58, v189, v89
	s_waitcnt lgkmcnt(0)
	v_add_f32_e32 v89, v89, v58
	ds_bpermute_b32 v58, v190, v89
	v_mfma_f32_16x16x32_bf16 v[192:195], v[62:65], v[142:145], 0
	v_mfma_f32_16x16x32_bf16 v[196:199], v[66:69], v[142:145], 0
	v_mfma_f32_16x16x32_bf16 v[200:203], v[70:73], v[142:145], 0
	v_mfma_f32_16x16x32_bf16 v[204:207], v[74:77], v[142:145], 0
	ds_read_b64_tr_b16 v[62:63], v236 offset:55296
	ds_read_b64_tr_b16 v[64:65], v237 offset:55296
	ds_read_b64_tr_b16 v[66:67], v236 offset:55304
	ds_read_b64_tr_b16 v[68:69], v237 offset:55304
	ds_read_b64_tr_b16 v[70:71], v236 offset:55360
	ds_read_b64_tr_b16 v[72:73], v237 offset:55360
	ds_read_b64_tr_b16 v[74:75], v236 offset:55368
	ds_read_b64_tr_b16 v[76:77], v237 offset:55368
	s_waitcnt lgkmcnt(8)
	v_add_f32_e32 v89, v89, v58
	v_mfma_f32_16x16x32_bf16 v[192:195], v[208:211], v[146:149], v[192:195]
	v_mfma_f32_16x16x32_bf16 v[196:199], v[212:215], v[146:149], v[196:199]
	v_mfma_f32_16x16x32_bf16 v[200:203], v[216:219], v[146:149], v[200:203]
	v_mfma_f32_16x16x32_bf16 v[204:207], v[220:223], v[146:149], v[204:207]
	ds_read_b64_tr_b16 v[208:209], v238 offset:55296
	ds_read_b64_tr_b16 v[210:211], v239 offset:55296
	ds_read_b64_tr_b16 v[212:213], v238 offset:55304
	ds_read_b64_tr_b16 v[214:215], v239 offset:55304
	ds_read_b64_tr_b16 v[216:217], v238 offset:55360
	ds_read_b64_tr_b16 v[218:219], v239 offset:55360
	ds_read_b64_tr_b16 v[220:221], v238 offset:55368
	ds_read_b64_tr_b16 v[222:223], v239 offset:55368
	s_waitcnt lgkmcnt(8)
	v_mfma_f32_16x16x32_bf16 v[192:195], v[62:65], v[150:153], v[192:195]
	v_mfma_f32_16x16x32_bf16 v[196:199], v[66:69], v[150:153], v[196:199]
	v_mfma_f32_16x16x32_bf16 v[200:203], v[70:73], v[150:153], v[200:203]
	v_mfma_f32_16x16x32_bf16 v[204:207], v[74:77], v[150:153], v[204:207]
	ds_read_b64_tr_b16 v[62:63], v240 offset:55296
	ds_read_b64_tr_b16 v[64:65], v241 offset:55296
	ds_read_b64_tr_b16 v[66:67], v240 offset:55304
	ds_read_b64_tr_b16 v[68:69], v241 offset:55304
	ds_read_b64_tr_b16 v[70:71], v240 offset:55360
	ds_read_b64_tr_b16 v[72:73], v241 offset:55360
	ds_read_b64_tr_b16 v[74:75], v240 offset:55368
	ds_read_b64_tr_b16 v[76:77], v241 offset:55368
	s_waitcnt lgkmcnt(8)
	v_mfma_f32_16x16x32_bf16 v[192:195], v[208:211], v[154:157], v[192:195]
	v_mfma_f32_16x16x32_bf16 v[196:199], v[212:215], v[154:157], v[196:199]
	v_mfma_f32_16x16x32_bf16 v[200:203], v[216:219], v[154:157], v[200:203]
	v_mfma_f32_16x16x32_bf16 v[204:207], v[220:223], v[154:157], v[204:207]
	s_waitcnt lgkmcnt(0)
	v_mfma_f32_16x16x32_bf16 v[192:195], v[62:65], v[162:165], v[192:195]
	v_mfma_f32_16x16x32_bf16 v[196:199], v[66:69], v[162:165], v[196:199]
	v_mfma_f32_16x16x32_bf16 v[200:203], v[70:73], v[162:165], v[200:203]
	v_mfma_f32_16x16x32_bf16 v[204:207], v[74:77], v[162:165], v[204:207]
	v_div_scale_f32 v58, s[34:35], v89, v89, 1.0
	v_rcp_f32_e32 v59, v58
	s_bfe_u32 s4, s99, 0x20000
	v_fma_f32 v61, -v58, v59, 1.0
	v_fmac_f32_e32 v59, v61, v59
	v_div_scale_f32 v61, vcc, 1.0, v89, 1.0
	v_mul_f32_e32 v92, v61, v59
	v_fma_f32 v93, -v58, v92, v61
	v_fmac_f32_e32 v92, v93, v59
	v_fma_f32 v58, -v58, v92, v61
	v_div_fmas_f32 v58, v58, v59, v92
	v_div_fixup_f32 v92, v58, v89, 1.0
	s_lshl_b32 s5, s4, 1
	s_bfe_u32 s15, s99, 0x80011
	s_lshr_b32 s34, s15, s5
	s_lshl_b32 s34, s34, 12
	s_bfm_b32 s35, s5, 0
	s_and_b32 s35, s35, s15
	s_add_i32 s34, s34, s35
	s_bfe_u32 s35, s99, 0x50006
	s_lshl_b32 s35, s35, 7
	s_add_i32 s35, s35, s33
	v_add_u32_e32 v58, s35, v185
	v_lshlrev_b32_e32 v58, s5, v58
	v_add_u32_e32 v58, s34, v58
	s_bfe_u32 s5, s99, 0x40002
	s_lshl_b32 s15, s5, 7
	v_lshl_add_u32 v59, v188, 1, s15
	v_lshl_add_u32 v59, v58, 11, v59
	s_mul_i32 s15, s4, 0x2100000
	s_add_i32 s15, s15, 0x23000000
	s_mov_b32 s16, s30
	v_pk_mul_f32 v[192:193], v[192:193], v[92:93] op_sel_hi:[1,0]
	v_pk_mul_f32 v[194:195], v[194:195], v[92:93] op_sel_hi:[1,0]
	v_pk_mul_f32 v[196:197], v[196:197], v[92:93] op_sel_hi:[1,0]
	v_pk_mul_f32 v[198:199], v[198:199], v[92:93] op_sel_hi:[1,0]
	v_pk_mul_f32 v[200:201], v[200:201], v[92:93] op_sel_hi:[1,0]
	v_pk_mul_f32 v[202:203], v[202:203], v[92:93] op_sel_hi:[1,0]
	v_pk_mul_f32 v[204:205], v[204:205], v[92:93] op_sel_hi:[1,0]
	v_pk_mul_f32 v[206:207], v[206:207], v[92:93] op_sel_hi:[1,0]
	v_cvt_pk_bf16_f32 v192, v192, v193
	v_cvt_pk_bf16_f32 v193, v194, v195
	v_cvt_pk_bf16_f32 v194, v196, v197
	v_cvt_pk_bf16_f32 v195, v198, v199
	v_cvt_pk_bf16_f32 v196, v200, v201
	v_cvt_pk_bf16_f32 v197, v202, v203
	v_cvt_pk_bf16_f32 v198, v204, v205
	v_cvt_pk_bf16_f32 v199, v206, v207
	buffer_store_dwordx4 v[192:195], v59, s[16:19], s15 offen
	buffer_store_dwordx4 v[196:199], v59, s[16:19], s15 offen offset:64
	v_log_f32_e32 v61, v89
	v_fma_f32 v86, -v91, v184, v86
	s_mul_i32 s15, s4, 0x4100
	v_add_u32_e32 v58, s15, v58
	v_add_f32_e32 v61, v86, v61
	s_lshl_b32 s15, s5, 2
	v_mul_f32_e32 v61, 0x3f317218, v61
	v_lshl_add_u32 v58, v58, 6, s15
	s_mov_b32 s15, 0x29300000
	s_mov_b64 exec, 0xffff
	buffer_store_dword v61, v58, s[16:19], s15 offen
	s_mov_b64 exec, -1
	s_bitcmp1_b32 s99, 26
	s_cbranch_scc1 .Lp9n_retA
	s_bitcmp1_b32 s99, 27
	s_cbranch_scc1 .Lp9n_retB
	s_bitcmp1_b32 s99, 28
	s_cbranch_scc1 .Lp9n_retC
	s_bitcmp1_b32 s99, 16
	s_cbranch_scc1 .Lat_retB
	s_bitset1_b32 s98, 1

.LBB0_1676:
	s_andn2_b64 vcc, exec, s[4:5]
	s_cbranch_vccnz .LBB0_1648
	s_bfe_u32 s99, s98, 0x10003
	s_bfe_u32 s100, s98, 0x10000
	s_bfe_u32 s101, s98, 0x10001
	s_add_u32 s99, s99, s101
	s_mul_i32 s99, s99, 3
	s_mul_i32 s100, s100, 6
	s_add_u32 s99, s99, s100
	s_cmp_eq_u32 s99, 12
	s_cbranch_scc1 .Lat_b12
	s_cmp_eq_u32 s99, 9
	s_cbranch_scc1 .Lat_b9
	s_cmp_eq_u32 s99, 6
	s_cbranch_scc1 .Lat_b6
	s_cmp_eq_u32 s99, 3
	s_cbranch_scc1 .Lat_b3
	s_waitcnt vmcnt(0)
	s_branch .Lat_bdone

; __device__ __forceinline__ bool att_step(int bid, int G, int ui, int s, int& grp, int& h, int& seq, int& blk, bool& comp) {
;     const int unit = bid + ui * G; if (unit >= 768) return false;
;     grp = unit >> 8; const int ul = unit & 255;
;     if (grp < 2) { const int strip = grp == 0 ? ul >> 2 : ul, qt0 = grp == 0 ? (ul & 3) * 8 : 0; h = strip & 15; seq = strip >> 4; blk = qt0 - 1 + s; comp = s > 0; }
;     else { const int strip = ul * 4 + s / 3, ss = s % 3; h = strip & 15; seq = strip >> 4; blk = ss - 1; comp = ss > 0; }
;     return true;
; }
; __device__ __forceinline__ void attn_tile(Frame& F, const __amdgpu_buffer_rsrc_t wsr, LAS unsigned char* L, int grp, int h, int seq, int blk, const bf16x8 (&qf)[2], int sl_prev, int sl_cur, int sl_next) {
;     const int lane = F.lane, w = F.wave, r = lane & 15, g4 = lane >> 4;
;     const int dsh = 2 * grp, q0 = blk * 128, qw0 = q0 + 16 * w;
;     ...
;     const float sl2 = alibi_slope2(grp, h) * (float)(1 << dsh);
;     const float b4 = sl2 * (float)(4 * g4);
;     f32x4 st[10];
; #pragma unroll
;     for (int Tg = 0; Tg < 3; ++Tg) {
;         bf16x8 kf[3][2];
; #pragma unroll
;         for (int i = 0; i < 3; ++i) { const int rb = 16 * w + 16 * (3 * Tg + i); const LAS unsigned char* kb = L + AT_K + SLOT3(rb >> 7) * AT_SLOT;
; #pragma unroll
;             for (int ks = 0; ks < 2; ++ks) kf[i][ks] = ldfrag(kb, (rb & 127) + r, P144, ks, g4); }
; #pragma unroll
;         for (int i = 0; i < 3; ++i) st[3 * Tg + i] = MFMA16(kf[i][0], qf[0], ((f32x4){b4, b4, b4, b4}));
; #pragma unroll
;         for (int i = 0; i < 3; ++i) st[3 * Tg + i] = MFMA16(kf[i][1], qf[1], st[3 * Tg + i]);
;     }
;     const int lo_ = max(r, 128 - qw0) - 4 * g4, hi_ = r + 128 - 4 * g4;
;     float mx = -INFINITY;
; #pragma unroll
;     for (int T = 0; T < 9; ++T)
; #pragma unroll
;         for (int e = 0; e < 4; ++e) { float y = __builtin_fmaf(sl2, (float)(16 * T + e), st[T][e]);
;             if ((16 * T + e) < lo_) y = -INFINITY;
;             if (T == 8) { if ((16 * T + e) > hi_) y = -INFINITY; }
;             st[T][e] = y; mx = fmaxf(mx, y); }
;     mx = fmaxf(mx, __shfl_xor(mx, 16)); mx = fmaxf(mx, __shfl_xor(mx, 32));
;     float lsum = 0.f;
; #pragma unroll
;     for (int T = 0; T < 9; ++T)
; #pragma unroll
;         for (int e = 0; e < 4; ++e) { const float p = __builtin_amdgcn_exp2f(st[T][e] - mx); st[T][e] = p; lsum += p; }
.Lp9n_entry:
	v_readfirstlane_b32 s33, v0
	s_mov_b32 s16, s30
	s_and_b32 s17, s31, 0xffff
	s_mov_b32 s18, 0x2b800000
	s_mov_b32 s19, 0x20000
	s_mov_b32 s95, 0x42400000
	s_lshr_b32 s33, s33, 6
	s_lshl_b32 s33, s33, 4
	v_and_b32_e32 v185, 15, v160
	v_lshrrev_b32_e32 v186, 4, v160
	v_lshlrev_b32_e32 v186, 2, v186
	v_mov_b32_e32 v191, 0xff800000
	v_mul_u32_u24_e32 v170, 0x90, v185
	v_lshl_add_u32 v170, v186, 2, v170
	v_lshrrev_b32_e32 v171, 2, v185
	v_add_u32_e32 v171, v171, v186
	v_mul_u32_u24_e32 v171, 0x90, v171
	v_and_b32_e32 v172, 3, v185
	v_lshl_add_u32 v171, v172, 4, v171
	v_cvt_f32_u32_e32 v172, v186
	v_add_f32_e32 v173, 1.0, v172
	v_add_f32_e32 v174, 2.0, v172
	v_add_f32_e32 v175, 1.0, v174
	v_add_u32_e32 v184, 0, v186
	v_cmp_lt_u32_e32 vcc, v184, v185
	s_nop 1
	v_cndmask_b32_e32 v176, 0, v191, vcc
	v_cmp_gt_u32_e32 vcc, v184, v185
	s_nop 1
	v_cndmask_b32_e32 v180, 0, v191, vcc
	v_add_u32_e32 v184, 1, v186
	v_cmp_lt_u32_e32 vcc, v184, v185
	s_nop 1
	v_cndmask_b32_e32 v177, 0, v191, vcc
	v_cmp_gt_u32_e32 vcc, v184, v185
	s_nop 1
	v_cndmask_b32_e32 v181, 0, v191, vcc
	v_add_u32_e32 v184, 2, v186
	v_cmp_lt_u32_e32 vcc, v184, v185
	s_nop 1
	v_cndmask_b32_e32 v178, 0, v191, vcc
	v_cmp_gt_u32_e32 vcc, v184, v185
	s_nop 1
	v_cndmask_b32_e32 v182, 0, v191, vcc
	v_add_u32_e32 v184, 3, v186
	v_cmp_lt_u32_e32 vcc, v184, v185
	s_nop 1
	v_cndmask_b32_e32 v179, 0, v191, vcc
	v_cmp_gt_u32_e32 vcc, v184, v185
	s_nop 1
	v_cndmask_b32_e32 v183, 0, v191, vcc
	v_add_u32_e32 v184, 0x80, v185
	v_cvt_f32_u32_e32 v184, v184
	v_subrev_u32_e32 v187, 24, v160
	v_min_u32_e32 v187, v160, v187
	v_mul_u32_u24_e32 v187, 0x900, v187
	v_lshlrev_b32_e32 v188, 1, v186
	v_xor_b32_e32 v189, 16, v160
	v_lshlrev_b32_e32 v189, 2, v189
	v_xor_b32_e32 v190, 32, v160
	v_lshlrev_b32_e32 v190, 2, v190
	v_lshrrev_b32_e32 v105, 3, v0
	v_and_b32_e32 v106, 7, v0
	v_mul_u32_u24_e32 v100, 0x90, v105
	v_lshl_add_u32 v100, v106, 4, v100
	v_lshlrev_b32_e32 v101, 4, v0
	v_add_u32_e32 v102, 0x2000, v101
	v_add_u32_e32 v103, s33, v185
	v_lshlrev_b32_e32 v103, 7, v103
	v_lshl_add_u32 v103, v186, 2, v103
	v_mov_b32_e32 v108, 0x80000000
	s_lshr_b32 s21, s2, 2
	s_and_b32 s22, s21, 15
	s_lshr_b32 s23, s21, 4
	s_and_b32 s24, s2, 3
	s_lshl_b32 s24, s24, 3
	s_lshl_b32 s25, s22, 2
	s_lshl_b32 s26, s23, 12
	s_or_b32 s25, s25, s26
	s_lshl_b32 s26, s24, 6
	s_or_b32 s25, s25, s26
	s_cmp_lg_u32 s24, 0
	s_cselect_b32 s26, 0x200000, 0
	s_or_b32 s26, s25, s26
	v_writelane_b32 v104, s26, 0
	s_add_i32 s26, s25, 3145792
	v_writelane_b32 v104, s26, 1
	s_add_i32 s26, s25, 3145856
	v_writelane_b32 v104, s26, 2
	s_add_i32 s26, s25, 3145920
	v_writelane_b32 v104, s26, 3
	s_add_i32 s26, s25, 3145984
	v_writelane_b32 v104, s26, 4
	s_add_i32 s26, s25, 3146048
	v_writelane_b32 v104, s26, 5
	s_add_i32 s26, s25, 3146112
	v_writelane_b32 v104, s26, 6
	s_add_i32 s26, s25, 3146176
	v_writelane_b32 v104, s26, 7
	s_add_i32 s26, s25, 3146240
	v_writelane_b32 v104, s26, 8
	s_and_b32 s22, s2, 15
	s_lshr_b32 s23, s2, 4
	s_lshl_b32 s25, s22, 2
	s_lshl_b32 s26, s23, 12
	s_or_b32 s25, s25, s26
	s_or_b32 s25, s25, 1
	v_writelane_b32 v104, s25, 9
	s_add_i32 s26, s25, 3145792
	v_writelane_b32 v104, s26, 10
	s_add_i32 s26, s25, 3145856
	v_writelane_b32 v104, s26, 11
	s_add_i32 s26, s25, 3145920
	v_writelane_b32 v104, s26, 12
	s_add_i32 s26, s25, 3145984
	v_writelane_b32 v104, s26, 13
	s_add_i32 s26, s25, 3146048
	v_writelane_b32 v104, s26, 14
	s_add_i32 s26, s25, 3146112
	v_writelane_b32 v104, s26, 15
	s_add_i32 s26, s25, 3146176
	v_writelane_b32 v104, s26, 16
	s_add_i32 s26, s25, 3146240
	v_writelane_b32 v104, s26, 17
	s_and_b32 s22, s2, 3
	s_lshl_b32 s22, s22, 2
	s_lshr_b32 s23, s2, 2
	s_lshl_b32 s26, s23, 12
	s_add_i32 s25, s22, 0
	s_lshl_b32 s25, s25, 2
	s_or_b32 s25, s25, s26
	s_or_b32 s25, s25, 2
	v_writelane_b32 v104, s25, 18
	s_add_i32 s27, s25, 3145792
	v_writelane_b32 v104, s27, 19
	s_add_i32 s27, s25, 3145856
	v_writelane_b32 v104, s27, 20
	s_add_i32 s25, s22, 1
	s_lshl_b32 s25, s25, 2
	s_or_b32 s25, s25, s26
	s_or_b32 s25, s25, 2
	v_writelane_b32 v104, s25, 21
	s_add_i32 s27, s25, 3145792
	v_writelane_b32 v104, s27, 22
	s_add_i32 s27, s25, 3145856
	v_writelane_b32 v104, s27, 23
	s_add_i32 s25, s22, 2
	s_lshl_b32 s25, s25, 2
	s_or_b32 s25, s25, s26
	s_or_b32 s25, s25, 2
	v_writelane_b32 v104, s25, 24
	s_add_i32 s27, s25, 3145792
	v_writelane_b32 v104, s27, 25
	s_add_i32 s27, s25, 3145856
	v_writelane_b32 v104, s27, 26
	s_add_i32 s25, s22, 3
	s_lshl_b32 s25, s25, 2
	s_or_b32 s25, s25, s26
	s_or_b32 s25, s25, 2
	v_writelane_b32 v104, s25, 27
	s_add_i32 s27, s25, 3145792
	v_writelane_b32 v104, s27, 28
	s_add_i32 s27, s25, 3145856
	v_writelane_b32 v104, s27, 29
	s_mov_b32 s25, 0
	v_writelane_b32 v104, s25, 30
	v_writelane_b32 v104, s25, 31
	v_writelane_b32 v104, s25, 32
	s_nop 1
	v_readlane_b32 s23, v104, 0
	s_nop 3
	s_bfe_u32 s36, s23, 0x20000
	s_bfe_u32 s37, s23, 0x40002
	s_bfe_u32 s38, s23, 0x60006
	s_bfe_u32 s39, s23, 0x8000c
	s_lshl_b32 s40, s36, 1
	s_lshr_b32 s40, 0x1000, s40
	s_mul_i32 s39, s39, s40
	s_add_i32 s38, s38, -1
	s_lshl_b32 s38, s38, 7
	s_add_i32 s39, s39, s38
	s_lshl_b32 s39, s39, 7
	s_mul_i32 s37, s37, 0x208000
	s_add_i32 s39, s39, s37
	s_bitcmp1_b32 s23, 21
	s_cselect_b32 s39, s39, 0x80000000
	s_mul_i32 s36, s36, 0x2100000
	s_add_i32 s40, s36, 0x16a00000
	s_add_i32 s41, s36, 0x1cd00000
	s_add_i32 s42, s36, 0x10700000
	v_add_u32_e32 v105, s39, v101
	v_add_u32_e32 v106, s39, v102
	v_add_u32_e32 v107, s39, v103
	buffer_load_dwordx4 v[26:29], v105, s[16:19], s40 offen nt
	buffer_load_dwordx4 v[30:33], v105, s[16:19], s41 offen nt
	buffer_load_dwordx4 v[34:37], v106, s[16:19], s40 offen nt
	buffer_load_dwordx4 v[38:41], v106, s[16:19], s41 offen nt
	buffer_load_dwordx4 v[2:5], v107, s[16:19], s42 offen nt
	buffer_load_dwordx4 v[6:9], v107, s[16:19], s42 offen offset:64 nt
	buffer_store_dword v108, v108, s[16:19], 0 offen
	buffer_store_dword v108, v108, s[16:19], 0 offen
	buffer_store_dword v108, v108, s[16:19], 0 offen
	v_readlane_b32 s23, v104, 1
	s_nop 3
	s_bfe_u32 s36, s23, 0x20000
	s_bfe_u32 s37, s23, 0x40002
	s_bfe_u32 s38, s23, 0x60006
	s_bfe_u32 s39, s23, 0x8000c
	s_lshl_b32 s40, s36, 1
	s_lshr_b32 s40, 0x1000, s40
	s_mul_i32 s39, s39, s40
	s_add_i32 s38, s38, -1
	s_lshl_b32 s38, s38, 7
	s_add_i32 s39, s39, s38
	s_lshl_b32 s39, s39, 7
	s_mul_i32 s37, s37, 0x208000
	s_add_i32 s39, s39, s37
	s_bitcmp1_b32 s23, 21
	s_cselect_b32 s39, s39, 0x80000000
	s_mul_i32 s36, s36, 0x2100000
	s_add_i32 s40, s36, 0x16a00000
	s_add_i32 s41, s36, 0x1cd00000
	s_add_i32 s42, s36, 0x10700000
	v_add_u32_e32 v105, s39, v101
	v_add_u32_e32 v106, s39, v102
	v_add_u32_e32 v107, s39, v103
	buffer_load_dwordx4 v[42:45], v105, s[16:19], s40 offen nt
	buffer_load_dwordx4 v[46:49], v105, s[16:19], s41 offen nt
	buffer_load_dwordx4 v[50:53], v106, s[16:19], s40 offen nt
	buffer_load_dwordx4 v[54:57], v106, s[16:19], s41 offen nt
	buffer_load_dwordx4 v[10:13], v107, s[16:19], s42 offen nt
	buffer_load_dwordx4 v[14:17], v107, s[16:19], s42 offen offset:64 nt
	buffer_store_dword v108, v108, s[16:19], 0 offen
	buffer_store_dword v108, v108, s[16:19], 0 offen
	buffer_store_dword v108, v108, s[16:19], 0 offen
	v_readlane_b32 s23, v104, 2
	s_nop 3
	s_bfe_u32 s36, s23, 0x20000
	s_bfe_u32 s37, s23, 0x40002
	s_bfe_u32 s38, s23, 0x60006
	s_bfe_u32 s39, s23, 0x8000c
	s_lshl_b32 s40, s36, 1
	s_lshr_b32 s40, 0x1000, s40
	s_mul_i32 s39, s39, s40
	s_add_i32 s38, s38, -1
	s_lshl_b32 s38, s38, 7
	s_add_i32 s39, s39, s38
	s_lshl_b32 s39, s39, 7
	s_mul_i32 s37, s37, 0x208000
	s_add_i32 s39, s39, s37
	s_bitcmp1_b32 s23, 21
	s_cselect_b32 s39, s39, 0x80000000
	s_mul_i32 s36, s36, 0x2100000
	s_add_i32 s40, s36, 0x16a00000
	s_add_i32 s41, s36, 0x1cd00000
	s_add_i32 s42, s36, 0x10700000
	v_add_u32_e32 v105, s39, v101
	v_add_u32_e32 v106, s39, v102
	v_add_u32_e32 v107, s39, v103
	buffer_load_dwordx4 v[110:113], v105, s[16:19], s40 offen nt
	buffer_load_dwordx4 v[114:117], v105, s[16:19], s41 offen nt
	buffer_load_dwordx4 v[118:121], v106, s[16:19], s40 offen nt
	buffer_load_dwordx4 v[122:125], v106, s[16:19], s41 offen nt
	buffer_load_dwordx4 v[126:129], v107, s[16:19], s42 offen nt
	buffer_load_dwordx4 v[130:133], v107, s[16:19], s42 offen offset:64 nt
	buffer_store_dword v108, v108, s[16:19], 0 offen
	buffer_store_dword v108, v108, s[16:19], 0 offen
	buffer_store_dword v108, v108, s[16:19], 0 offen
	s_mov_b32 s20, 0
	s_mov_b32 s21, 0
	.p2align 6
.Lp9n_loop:
.Lp9n_stepA:
	s_add_i32 s23, s20, 3
	v_readlane_b32 s22, v104, s20
	v_readlane_b32 s23, v104, s23
	s_mul_i32 s24, s21, 0x4800
	s_waitcnt vmcnt(21)
	v_add_u32_e32 v109, s24, v100
	ds_write_b128 v109, v[26:29]
	ds_write_b128 v109, v[30:33] offset:55296
	ds_write_b128 v109, v[34:37] offset:9216
	ds_write_b128 v109, v[38:41] offset:64512
	v_mov_b64_e32 v[18:19], v[2:3]
	v_mov_b64_e32 v[20:21], v[4:5]
	v_mov_b64_e32 v[22:23], v[6:7]
	v_mov_b64_e32 v[24:25], v[8:9]
	s_waitcnt lgkmcnt(0)
	s_barrier
	s_bfe_u32 s36, s23, 0x20000
	s_bfe_u32 s37, s23, 0x40002
	s_bfe_u32 s38, s23, 0x60006
	s_bfe_u32 s39, s23, 0x8000c
	s_lshl_b32 s40, s36, 1
	s_lshr_b32 s40, 0x1000, s40
	s_mul_i32 s39, s39, s40
	s_add_i32 s38, s38, -1
	s_lshl_b32 s38, s38, 7
	s_add_i32 s39, s39, s38
	s_lshl_b32 s39, s39, 7
	s_mul_i32 s37, s37, 0x208000
	s_add_i32 s39, s39, s37
	s_bitcmp1_b32 s23, 21
	s_cselect_b32 s39, s39, 0x80000000
	s_mul_i32 s36, s36, 0x2100000
	s_add_i32 s40, s36, 0x16a00000
	s_add_i32 s41, s36, 0x1cd00000
	s_add_i32 s42, s36, 0x10700000
	v_add_u32_e32 v105, s39, v101
	v_add_u32_e32 v106, s39, v102
	v_add_u32_e32 v107, s39, v103
	s_bitcmp1_b32 s22, 20
	s_cbranch_scc0 .Lp9n_nocompA
	s_and_b32 s99, s22, 63
	s_bfe_u32 s4, s22, 0x60006
	s_add_i32 s4, s4, -1
	s_lshl_b32 s4, s4, 6
	s_or_b32 s99, s99, s4
	s_add_i32 s4, s21, -1
	s_cmp_lt_i32 s4, 0
	s_cselect_b32 s4, 2, s4
	s_lshl_b32 s4, s4, 3
	s_lshr_b32 s5, s33, 4
	s_add_i32 s4, s4, s5
	s_lshl_b32 s4, s4, 11
	s_or_b32 s99, s99, s4
	s_bfe_u32 s4, s22, 0x8000c
	s_lshl_b32 s4, s4, 17
	s_or_b32 s99, s99, s4
	buffer_load_dwordx4 v[26:29], v105, s[16:19], s40 offen nt
	buffer_load_dwordx4 v[30:33], v105, s[16:19], s41 offen nt
	buffer_load_dwordx4 v[34:37], v106, s[16:19], s40 offen nt
	buffer_load_dwordx4 v[38:41], v106, s[16:19], s41 offen nt
	buffer_load_dwordx4 v[2:5], v107, s[16:19], s42 offen nt
	buffer_load_dwordx4 v[6:9], v107, s[16:19], s42 offen offset:64 nt
	s_bitset1_b32 s99, 26
	s_branch .Lat_tile
.Lp9n_nocompA:
	buffer_load_dwordx4 v[26:29], v105, s[16:19], s40 offen nt
	buffer_load_dwordx4 v[30:33], v105, s[16:19], s41 offen nt
	buffer_load_dwordx4 v[34:37], v106, s[16:19], s40 offen nt
	buffer_load_dwordx4 v[38:41], v106, s[16:19], s41 offen nt
	buffer_load_dwordx4 v[2:5], v107, s[16:19], s42 offen nt
	buffer_load_dwordx4 v[6:9], v107, s[16:19], s42 offen offset:64 nt
	buffer_store_dword v108, v108, s[16:19], 0 offen
	buffer_store_dword v108, v108, s[16:19], 0 offen
	buffer_store_dword v108, v108, s[16:19], 0 offen
.Lp9n_retA:
	s_add_i32 s20, s20, 1
	s_add_i32 s21, s21, 1
	s_cmp_eq_u32 s21, 3
	s_cselect_b32 s21, 0, s21
.Lp9n_stepB:
	s_add_i32 s23, s20, 3
	v_readlane_b32 s22, v104, s20
	v_readlane_b32 s23, v104, s23
	s_mul_i32 s24, s21, 0x4800
	s_waitcnt vmcnt(21)
	v_add_u32_e32 v109, s24, v100
	ds_write_b128 v109, v[42:45]
	ds_write_b128 v109, v[46:49] offset:55296
	ds_write_b128 v109, v[50:53] offset:9216
	ds_write_b128 v109, v[54:57] offset:64512
	v_mov_b64_e32 v[18:19], v[10:11]
	v_mov_b64_e32 v[20:21], v[12:13]
	v_mov_b64_e32 v[22:23], v[14:15]
	v_mov_b64_e32 v[24:25], v[16:17]
	s_waitcnt lgkmcnt(0)
	s_barrier
	s_bfe_u32 s36, s23, 0x20000
	s_bfe_u32 s37, s23, 0x40002
	s_bfe_u32 s38, s23, 0x60006
	s_bfe_u32 s39, s23, 0x8000c
	s_lshl_b32 s40, s36, 1
	s_lshr_b32 s40, 0x1000, s40
	s_mul_i32 s39, s39, s40
	s_add_i32 s38, s38, -1
	s_lshl_b32 s38, s38, 7
	s_add_i32 s39, s39, s38
	s_lshl_b32 s39, s39, 7
	s_mul_i32 s37, s37, 0x208000
	s_add_i32 s39, s39, s37
	s_bitcmp1_b32 s23, 21
	s_cselect_b32 s39, s39, 0x80000000
	s_mul_i32 s36, s36, 0x2100000
	s_add_i32 s40, s36, 0x16a00000
	s_add_i32 s41, s36, 0x1cd00000
	s_add_i32 s42, s36, 0x10700000
	v_add_u32_e32 v105, s39, v101
	v_add_u32_e32 v106, s39, v102
	v_add_u32_e32 v107, s39, v103
	s_bitcmp1_b32 s22, 20
	s_cbranch_scc0 .Lp9n_nocompB
	s_and_b32 s99, s22, 63
	s_bfe_u32 s4, s22, 0x60006
	s_add_i32 s4, s4, -1
	s_lshl_b32 s4, s4, 6
	s_or_b32 s99, s99, s4
	s_add_i32 s4, s21, -1
	s_cmp_lt_i32 s4, 0
	s_cselect_b32 s4, 2, s4
	s_lshl_b32 s4, s4, 3
	s_lshr_b32 s5, s33, 4
	s_add_i32 s4, s4, s5
	s_lshl_b32 s4, s4, 11
	s_or_b32 s99, s99, s4
	s_bfe_u32 s4, s22, 0x8000c
	s_lshl_b32 s4, s4, 17
	s_or_b32 s99, s99, s4
	buffer_load_dwordx4 v[42:45], v105, s[16:19], s40 offen nt
	buffer_load_dwordx4 v[46:49], v105, s[16:19], s41 offen nt
	buffer_load_dwordx4 v[50:53], v106, s[16:19], s40 offen nt
	buffer_load_dwordx4 v[54:57], v106, s[16:19], s41 offen nt
	buffer_load_dwordx4 v[10:13], v107, s[16:19], s42 offen nt
	buffer_load_dwordx4 v[14:17], v107, s[16:19], s42 offen offset:64 nt
	s_bitset1_b32 s99, 27
	s_branch .Lat_tile
.Lp9n_nocompB:
	buffer_load_dwordx4 v[42:45], v105, s[16:19], s40 offen nt
	buffer_load_dwordx4 v[46:49], v105, s[16:19], s41 offen nt
	buffer_load_dwordx4 v[50:53], v106, s[16:19], s40 offen nt
	buffer_load_dwordx4 v[54:57], v106, s[16:19], s41 offen nt
	buffer_load_dwordx4 v[10:13], v107, s[16:19], s42 offen nt
	buffer_load_dwordx4 v[14:17], v107, s[16:19], s42 offen offset:64 nt
	buffer_store_dword v108, v108, s[16:19], 0 offen
	buffer_store_dword v108, v108, s[16:19], 0 offen
	buffer_store_dword v108, v108, s[16:19], 0 offen
.Lp9n_retB:
	s_add_i32 s20, s20, 1
	s_add_i32 s21, s21, 1
	s_cmp_eq_u32 s21, 3
	s_cselect_b32 s21, 0, s21
.Lp9n_stepC:
	s_add_i32 s23, s20, 3
	v_readlane_b32 s22, v104, s20
	v_readlane_b32 s23, v104, s23
	s_mul_i32 s24, s21, 0x4800
	s_waitcnt vmcnt(21)
	v_add_u32_e32 v109, s24, v100
	ds_write_b128 v109, v[110:113]
	ds_write_b128 v109, v[114:117] offset:55296
	ds_write_b128 v109, v[118:121] offset:9216
	ds_write_b128 v109, v[122:125] offset:64512
	v_mov_b64_e32 v[18:19], v[126:127]
	v_mov_b64_e32 v[20:21], v[128:129]
	v_mov_b64_e32 v[22:23], v[130:131]
	v_mov_b64_e32 v[24:25], v[132:133]
	s_waitcnt lgkmcnt(0)
	s_barrier
	s_bfe_u32 s36, s23, 0x20000
	s_bfe_u32 s37, s23, 0x40002
	s_bfe_u32 s38, s23, 0x60006
	s_bfe_u32 s39, s23, 0x8000c
	s_lshl_b32 s40, s36, 1
	s_lshr_b32 s40, 0x1000, s40
	s_mul_i32 s39, s39, s40
	s_add_i32 s38, s38, -1
	s_lshl_b32 s38, s38, 7
	s_add_i32 s39, s39, s38
	s_lshl_b32 s39, s39, 7
	s_mul_i32 s37, s37, 0x208000
	s_add_i32 s39, s39, s37
	s_bitcmp1_b32 s23, 21
	s_cselect_b32 s39, s39, 0x80000000
	s_mul_i32 s36, s36, 0x2100000
	s_add_i32 s40, s36, 0x16a00000
	s_add_i32 s41, s36, 0x1cd00000
	s_add_i32 s42, s36, 0x10700000
	v_add_u32_e32 v105, s39, v101
	v_add_u32_e32 v106, s39, v102
	v_add_u32_e32 v107, s39, v103
	s_bitcmp1_b32 s22, 20
	s_cbranch_scc0 .Lp9n_nocompC
	s_and_b32 s99, s22, 63
	s_bfe_u32 s4, s22, 0x60006
	s_add_i32 s4, s4, -1
	s_lshl_b32 s4, s4, 6
	s_or_b32 s99, s99, s4
	s_add_i32 s4, s21, -1
	s_cmp_lt_i32 s4, 0
	s_cselect_b32 s4, 2, s4
	s_lshl_b32 s4, s4, 3
	s_lshr_b32 s5, s33, 4
	s_add_i32 s4, s4, s5
	s_lshl_b32 s4, s4, 11
	s_or_b32 s99, s99, s4
	s_bfe_u32 s4, s22, 0x8000c
	s_lshl_b32 s4, s4, 17
	s_or_b32 s99, s99, s4
	buffer_load_dwordx4 v[110:113], v105, s[16:19], s40 offen nt
	buffer_load_dwordx4 v[114:117], v105, s[16:19], s41 offen nt
	buffer_load_dwordx4 v[118:121], v106, s[16:19], s40 offen nt
	buffer_load_dwordx4 v[122:125], v106, s[16:19], s41 offen nt
	buffer_load_dwordx4 v[126:129], v107, s[16:19], s42 offen nt
	buffer_load_dwordx4 v[130:133], v107, s[16:19], s42 offen offset:64 nt
	s_bitset1_b32 s99, 28
	s_branch .Lat_tile
.Lp9n_nocompC:
	buffer_load_dwordx4 v[110:113], v105, s[16:19], s40 offen nt
	buffer_load_dwordx4 v[114:117], v105, s[16:19], s41 offen nt
	buffer_load_dwordx4 v[118:121], v106, s[16:19], s40 offen nt
	buffer_load_dwordx4 v[122:125], v106, s[16:19], s41 offen nt
	buffer_load_dwordx4 v[126:129], v107, s[16:19], s42 offen nt
	buffer_load_dwordx4 v[130:133], v107, s[16:19], s42 offen offset:64 nt
	buffer_store_dword v108, v108, s[16:19], 0 offen
	buffer_store_dword v108, v108, s[16:19], 0 offen
	buffer_store_dword v108, v108, s[16:19], 0 offen
.Lp9n_retC:
	s_add_i32 s20, s20, 1
	s_add_i32 s21, s21, 1
	s_cmp_eq_u32 s21, 3
	s_cselect_b32 s21, 0, s21
	s_cmp_lt_u32 s20, 30
	s_cbranch_scc1 .Lp9n_loop
